# v85 with conversion waits counting younger LOADS only (safe even if stores retire ahead of older loads)
# speedup vs baseline: 1.0013x; 1.0013x over previous
.LBB0_332:
	s_abs_i32 s0, s33
	s_waitcnt vmcnt(34)
	v_cvt_f32_u32_e32 v1, s0
	s_sub_i32 s1, 0, s0
	v_rcp_iflag_f32_e32 v1, v1
	s_nop 0
	v_mul_f32_e32 v1, 0x4f7ffffe, v1
	v_cvt_u32_f32_e32 v1, v1
	s_nop 0
	v_readfirstlane_b32 s3, v1
	s_mul_i32 s1, s1, s3
	s_mul_hi_u32 s1, s3, s1
	s_add_i32 s3, s3, s1
	s_mul_hi_u32 s1, s3, 0x480
	s_mul_i32 s1, s1, s0
	s_sub_i32 s1, 0x480, s1
	s_sub_i32 s3, s1, s0
	s_cmp_ge_u32 s1, s0
	s_cselect_b32 s1, s3, s1
	s_sub_i32 s3, s1, s0
	s_cmp_ge_u32 s1, s0
	s_cselect_b32 s10, s3, s1
	v_readlane_b32 s0, v254, 2
	s_sub_i32 s0, s0, s10
	s_cmp_lt_i32 s0, 0
	s_cbranch_scc1 .Lconv_classA
	s_lshl_b32 s0, s0, 3
	s_add_i32 s0, s0, s78
	v_readlane_b32 s70, v254, 0
	v_readlane_b32 s71, v254, 1
	s_sub_u32 s70, s70, 0xc8
	s_subb_u32 s71, s71, 0
	s_load_dwordx4 s[4:7], s[70:71], 0x68
	s_load_dwordx2 s[8:9], s[70:71], 0x78
	s_load_dwordx2 s[10:11], s[70:71], 0x90
	s_add_u32 s12, s26, 0x2600000
	s_addc_u32 s13, s27, 0
	s_add_u32 s30, s26, 0x3200000
	s_addc_u32 s31, s27, 0
	s_add_u32 s42, s26, 0x3a00000
	s_addc_u32 s43, s27, 0
	v_and_b32_e32 v7, 63, v0
	v_lshrrev_b32_e32 v8, 3, v7
	v_and_b32_e32 v9, 7, v7
	v_lshlrev_b32_e32 v1, 13, v8
	v_lshl_add_u32 v1, v9, 4, v1
	v_mul_u32_u24_e32 v2, 0xb000, v8
	v_lshl_add_u32 v2, v9, 4, v2
	s_lshl_b32 s1, s78, 14
	v_mul_u32_u24_e32 v3, 33, v8
	v_lshl_add_u32 v3, v9, 2, v3
	v_lshl_add_u32 v3, v3, 2, s1
	v_mul_u32_u24_e32 v4, 0x108, v9
	v_add_u32_e32 v4, v4, v8
	v_lshl_add_u32 v4, v4, 2, s1
	v_mul_u32_u24_e32 v5, 0x1800, v8
	v_lshl_add_u32 v5, v9, 4, v5
	v_lshlrev_b32_e32 v6, 12, v8
	v_lshl_add_u32 v6, v9, 4, v6
	s_waitcnt lgkmcnt(0)
	s_mov_b32 s3, s0
	s_lshr_b32 s29, s3, 6
	s_and_b32 s35, s3, 63
	s_lshl_b32 s58, s29, 19
	s_lshl_b32 s59, s35, 7
	s_add_u32 s58, s58, s59
	s_add_u32 s46, s4, s58
	s_addc_u32 s47, s5, 0
	global_load_dwordx4 v[16:19], v1, s[46:47] nt
	v_add_u32_e32 v7, 0x10000, v1
	global_load_dwordx4 v[20:23], v7, s[46:47] nt
	v_add_u32_e32 v7, 0x20000, v1
	global_load_dwordx4 v[24:27], v7, s[46:47] nt
	v_add_u32_e32 v7, 0x30000, v1
	global_load_dwordx4 v[28:31], v7, s[46:47] nt
	v_add_u32_e32 v7, 0x40000, v1
	global_load_dwordx4 v[32:35], v7, s[46:47] nt
	v_add_u32_e32 v7, 0x50000, v1
	global_load_dwordx4 v[36:39], v7, s[46:47] nt
	v_add_u32_e32 v7, 0x60000, v1
	global_load_dwordx4 v[40:43], v7, s[46:47] nt
	v_add_u32_e32 v7, 0x70000, v1
	global_load_dwordx4 v[44:47], v7, s[46:47] nt
	s_add_i32 s3, s0, 1024
	s_lshr_b32 s29, s3, 6
	s_and_b32 s35, s3, 63
	s_lshl_b32 s58, s29, 19
	s_lshl_b32 s59, s35, 7
	s_add_u32 s58, s58, s59
	s_add_u32 s46, s4, s58
	s_addc_u32 s47, s5, 0
	global_load_dwordx4 v[48:51], v1, s[46:47] nt
	v_add_u32_e32 v7, 0x10000, v1
	global_load_dwordx4 v[52:55], v7, s[46:47] nt
	v_add_u32_e32 v7, 0x20000, v1
	global_load_dwordx4 v[56:59], v7, s[46:47] nt
	v_add_u32_e32 v7, 0x30000, v1
	global_load_dwordx4 v[60:63], v7, s[46:47] nt
	v_add_u32_e32 v7, 0x40000, v1
	global_load_dwordx4 v[64:67], v7, s[46:47] nt
	v_add_u32_e32 v7, 0x50000, v1
	global_load_dwordx4 v[68:71], v7, s[46:47] nt
	v_add_u32_e32 v7, 0x60000, v1
	global_load_dwordx4 v[72:75], v7, s[46:47] nt
	v_add_u32_e32 v7, 0x70000, v1
	global_load_dwordx4 v[76:79], v7, s[46:47] nt
	s_mov_b32 s3, s0
	s_lshr_b32 s29, s3, 6
	s_and_b32 s35, s3, 63
	s_lshl_b32 s58, s29, 19
	s_lshl_b32 s59, s35, 7
	s_add_u32 s58, s58, s59
	s_add_u32 s46, s6, s58
	s_addc_u32 s47, s7, 0
	global_load_dwordx4 v[80:83], v1, s[46:47] nt
	v_add_u32_e32 v7, 0x10000, v1
	global_load_dwordx4 v[84:87], v7, s[46:47] nt
	v_add_u32_e32 v7, 0x20000, v1
	global_load_dwordx4 v[88:91], v7, s[46:47] nt
	v_add_u32_e32 v7, 0x30000, v1
	global_load_dwordx4 v[92:95], v7, s[46:47] nt
	v_add_u32_e32 v7, 0x40000, v1
	global_load_dwordx4 v[96:99], v7, s[46:47] nt
	v_add_u32_e32 v7, 0x50000, v1
	global_load_dwordx4 v[100:103], v7, s[46:47] nt
	v_add_u32_e32 v7, 0x60000, v1
	global_load_dwordx4 v[104:107], v7, s[46:47] nt
	v_add_u32_e32 v7, 0x70000, v1
	global_load_dwordx4 v[108:111], v7, s[46:47] nt
	s_waitcnt vmcnt(16)
	ds_write_b32 v3, v16
	ds_write_b32 v3, v17 offset:4
	ds_write_b32 v3, v18 offset:8
	ds_write_b32 v3, v19 offset:12
	ds_write_b32 v3, v20 offset:1056
	ds_write_b32 v3, v21 offset:1060
	ds_write_b32 v3, v22 offset:1064
	ds_write_b32 v3, v23 offset:1068
	ds_write_b32 v3, v24 offset:2112
	ds_write_b32 v3, v25 offset:2116
	ds_write_b32 v3, v26 offset:2120
	ds_write_b32 v3, v27 offset:2124
	ds_write_b32 v3, v28 offset:3168
	ds_write_b32 v3, v29 offset:3172
	ds_write_b32 v3, v30 offset:3176
	ds_write_b32 v3, v31 offset:3180
	ds_write_b32 v3, v32 offset:4224
	ds_write_b32 v3, v33 offset:4228
	ds_write_b32 v3, v34 offset:4232
	ds_write_b32 v3, v35 offset:4236
	ds_write_b32 v3, v36 offset:5280
	ds_write_b32 v3, v37 offset:5284
	ds_write_b32 v3, v38 offset:5288
	ds_write_b32 v3, v39 offset:5292
	ds_write_b32 v3, v40 offset:6336
	ds_write_b32 v3, v41 offset:6340
	ds_write_b32 v3, v42 offset:6344
	ds_write_b32 v3, v43 offset:6348
	ds_write_b32 v3, v44 offset:7392
	ds_write_b32 v3, v45 offset:7396
	ds_write_b32 v3, v46 offset:7400
	ds_write_b32 v3, v47 offset:7404
	s_waitcnt lgkmcnt(0)
	s_mov_b32 s3, s0
	s_lshr_b32 s29, s3, 6
	s_and_b32 s35, s3, 63
	s_mul_i32 s58, s35, 0x30000
	s_lshl_b32 s59, s29, 7
	s_add_u32 s58, s58, s59
	s_add_u32 s48, s12, s58
	s_addc_u32 s49, s13, 0
	ds_read2_b32 v[8:9], v4 offset0:0 offset1:33
	ds_read2_b32 v[10:11], v4 offset0:66 offset1:99
	ds_read2_b32 v[12:13], v4 offset0:132 offset1:165
	ds_read2_b32 v[14:15], v4 offset0:198 offset1:231
	s_waitcnt lgkmcnt(0)
	v_cvt_pk_bf16_f32 v16, v8, v9
	v_cvt_pk_bf16_f32 v17, v10, v11
	v_cvt_pk_bf16_f32 v18, v12, v13
	v_cvt_pk_bf16_f32 v19, v14, v15
	global_store_dwordx4 v5, v[16:19], s[48:49]
	ds_read2_b32 v[8:9], v4 offset0:8 offset1:41
	ds_read2_b32 v[10:11], v4 offset0:74 offset1:107
	ds_read2_b32 v[12:13], v4 offset0:140 offset1:173
	ds_read2_b32 v[14:15], v4 offset0:206 offset1:239
	s_waitcnt lgkmcnt(0)
	v_cvt_pk_bf16_f32 v20, v8, v9
	v_cvt_pk_bf16_f32 v21, v10, v11
	v_cvt_pk_bf16_f32 v22, v12, v13
	v_cvt_pk_bf16_f32 v23, v14, v15
	v_add_u32_e32 v7, 0xc000, v5
	global_store_dwordx4 v7, v[20:23], s[48:49]
	ds_read2_b32 v[8:9], v4 offset0:16 offset1:49
	ds_read2_b32 v[10:11], v4 offset0:82 offset1:115
	ds_read2_b32 v[12:13], v4 offset0:148 offset1:181
	ds_read2_b32 v[14:15], v4 offset0:214 offset1:247
	s_waitcnt lgkmcnt(0)
	v_cvt_pk_bf16_f32 v24, v8, v9
	v_cvt_pk_bf16_f32 v25, v10, v11
	v_cvt_pk_bf16_f32 v26, v12, v13
	v_cvt_pk_bf16_f32 v27, v14, v15
	v_add_u32_e32 v7, 0x18000, v5
	global_store_dwordx4 v7, v[24:27], s[48:49]
	ds_read2_b32 v[8:9], v4 offset0:24 offset1:57
	ds_read2_b32 v[10:11], v4 offset0:90 offset1:123
	ds_read2_b32 v[12:13], v4 offset0:156 offset1:189
	ds_read2_b32 v[14:15], v4 offset0:222 offset1:255
	s_waitcnt lgkmcnt(0)
	v_cvt_pk_bf16_f32 v28, v8, v9
	v_cvt_pk_bf16_f32 v29, v10, v11
	v_cvt_pk_bf16_f32 v30, v12, v13
	v_cvt_pk_bf16_f32 v31, v14, v15
	v_add_u32_e32 v7, 0x24000, v5
	global_store_dwordx4 v7, v[28:31], s[48:49]
	s_mov_b32 s3, s0
	s_lshr_b32 s29, s3, 6
	s_and_b32 s35, s3, 63
	s_lshl_b32 s58, s29, 19
	s_lshl_b32 s59, s35, 7
	s_add_u32 s58, s58, s59
	s_add_u32 s46, s8, s58
	s_addc_u32 s47, s9, 0
	global_load_dwordx4 v[16:19], v1, s[46:47] nt
	v_add_u32_e32 v7, 0x10000, v1
	global_load_dwordx4 v[20:23], v7, s[46:47] nt
	v_add_u32_e32 v7, 0x20000, v1
	global_load_dwordx4 v[24:27], v7, s[46:47] nt
	v_add_u32_e32 v7, 0x30000, v1
	global_load_dwordx4 v[28:31], v7, s[46:47] nt
	v_add_u32_e32 v7, 0x40000, v1
	global_load_dwordx4 v[32:35], v7, s[46:47] nt
	v_add_u32_e32 v7, 0x50000, v1
	global_load_dwordx4 v[36:39], v7, s[46:47] nt
	v_add_u32_e32 v7, 0x60000, v1
	global_load_dwordx4 v[40:43], v7, s[46:47] nt
	v_add_u32_e32 v7, 0x70000, v1
	global_load_dwordx4 v[44:47], v7, s[46:47] nt
	s_waitcnt vmcnt(16)
	ds_write_b32 v3, v48
	ds_write_b32 v3, v49 offset:4
	ds_write_b32 v3, v50 offset:8
	ds_write_b32 v3, v51 offset:12
	ds_write_b32 v3, v52 offset:1056
	ds_write_b32 v3, v53 offset:1060
	ds_write_b32 v3, v54 offset:1064
	ds_write_b32 v3, v55 offset:1068
	ds_write_b32 v3, v56 offset:2112
	ds_write_b32 v3, v57 offset:2116
	ds_write_b32 v3, v58 offset:2120
	ds_write_b32 v3, v59 offset:2124
	ds_write_b32 v3, v60 offset:3168
	ds_write_b32 v3, v61 offset:3172
	ds_write_b32 v3, v62 offset:3176
	ds_write_b32 v3, v63 offset:3180
	ds_write_b32 v3, v64 offset:4224
	ds_write_b32 v3, v65 offset:4228
	ds_write_b32 v3, v66 offset:4232
	ds_write_b32 v3, v67 offset:4236
	ds_write_b32 v3, v68 offset:5280
	ds_write_b32 v3, v69 offset:5284
	ds_write_b32 v3, v70 offset:5288
	ds_write_b32 v3, v71 offset:5292
	ds_write_b32 v3, v72 offset:6336
	ds_write_b32 v3, v73 offset:6340
	ds_write_b32 v3, v74 offset:6344
	ds_write_b32 v3, v75 offset:6348
	ds_write_b32 v3, v76 offset:7392
	ds_write_b32 v3, v77 offset:7396
	ds_write_b32 v3, v78 offset:7400
	ds_write_b32 v3, v79 offset:7404
	s_waitcnt lgkmcnt(0)
	s_add_i32 s3, s0, 1024
	s_lshr_b32 s29, s3, 6
	s_and_b32 s35, s3, 63
	s_mul_i32 s58, s35, 0x30000
	s_lshl_b32 s59, s29, 7
	s_add_u32 s58, s58, s59
	s_add_u32 s48, s12, s58
	s_addc_u32 s49, s13, 0
	ds_read2_b32 v[8:9], v4 offset0:0 offset1:33
	ds_read2_b32 v[10:11], v4 offset0:66 offset1:99
	ds_read2_b32 v[12:13], v4 offset0:132 offset1:165
	ds_read2_b32 v[14:15], v4 offset0:198 offset1:231
	s_waitcnt lgkmcnt(0)
	v_cvt_pk_bf16_f32 v48, v8, v9
	v_cvt_pk_bf16_f32 v49, v10, v11
	v_cvt_pk_bf16_f32 v50, v12, v13
	v_cvt_pk_bf16_f32 v51, v14, v15
	global_store_dwordx4 v5, v[48:51], s[48:49]
	ds_read2_b32 v[8:9], v4 offset0:8 offset1:41
	ds_read2_b32 v[10:11], v4 offset0:74 offset1:107
	ds_read2_b32 v[12:13], v4 offset0:140 offset1:173
	ds_read2_b32 v[14:15], v4 offset0:206 offset1:239
	s_waitcnt lgkmcnt(0)
	v_cvt_pk_bf16_f32 v52, v8, v9
	v_cvt_pk_bf16_f32 v53, v10, v11
	v_cvt_pk_bf16_f32 v54, v12, v13
	v_cvt_pk_bf16_f32 v55, v14, v15
	v_add_u32_e32 v7, 0xc000, v5
	global_store_dwordx4 v7, v[52:55], s[48:49]
	ds_read2_b32 v[8:9], v4 offset0:16 offset1:49
	ds_read2_b32 v[10:11], v4 offset0:82 offset1:115
	ds_read2_b32 v[12:13], v4 offset0:148 offset1:181
	ds_read2_b32 v[14:15], v4 offset0:214 offset1:247
	s_waitcnt lgkmcnt(0)
	v_cvt_pk_bf16_f32 v56, v8, v9
	v_cvt_pk_bf16_f32 v57, v10, v11
	v_cvt_pk_bf16_f32 v58, v12, v13
	v_cvt_pk_bf16_f32 v59, v14, v15
	v_add_u32_e32 v7, 0x18000, v5
	global_store_dwordx4 v7, v[56:59], s[48:49]
	ds_read2_b32 v[8:9], v4 offset0:24 offset1:57
	ds_read2_b32 v[10:11], v4 offset0:90 offset1:123
	ds_read2_b32 v[12:13], v4 offset0:156 offset1:189
	ds_read2_b32 v[14:15], v4 offset0:222 offset1:255
	s_waitcnt lgkmcnt(0)
	v_cvt_pk_bf16_f32 v60, v8, v9
	v_cvt_pk_bf16_f32 v61, v10, v11
	v_cvt_pk_bf16_f32 v62, v12, v13
	v_cvt_pk_bf16_f32 v63, v14, v15
	v_add_u32_e32 v7, 0x24000, v5
	global_store_dwordx4 v7, v[60:63], s[48:49]
	s_add_i32 s3, s0, 1024
	s_lshr_b32 s29, s3, 6
	s_and_b32 s35, s3, 63
	s_lshl_b32 s58, s29, 19
	s_lshl_b32 s59, s35, 7
	s_add_u32 s58, s58, s59
	s_add_u32 s46, s8, s58
	s_addc_u32 s47, s9, 0
	global_load_dwordx4 v[48:51], v1, s[46:47] nt
	v_add_u32_e32 v7, 0x10000, v1
	global_load_dwordx4 v[52:55], v7, s[46:47] nt
	v_add_u32_e32 v7, 0x20000, v1
	global_load_dwordx4 v[56:59], v7, s[46:47] nt
	v_add_u32_e32 v7, 0x30000, v1
	global_load_dwordx4 v[60:63], v7, s[46:47] nt
	v_add_u32_e32 v7, 0x40000, v1
	global_load_dwordx4 v[64:67], v7, s[46:47] nt
	v_add_u32_e32 v7, 0x50000, v1
	global_load_dwordx4 v[68:71], v7, s[46:47] nt
	v_add_u32_e32 v7, 0x60000, v1
	global_load_dwordx4 v[72:75], v7, s[46:47] nt
	v_add_u32_e32 v7, 0x70000, v1
	global_load_dwordx4 v[76:79], v7, s[46:47] nt
	s_waitcnt vmcnt(16)
	ds_write_b32 v3, v80
	ds_write_b32 v3, v81 offset:4
	ds_write_b32 v3, v82 offset:8
	ds_write_b32 v3, v83 offset:12
	ds_write_b32 v3, v84 offset:1056
	ds_write_b32 v3, v85 offset:1060
	ds_write_b32 v3, v86 offset:1064
	ds_write_b32 v3, v87 offset:1068
	ds_write_b32 v3, v88 offset:2112
	ds_write_b32 v3, v89 offset:2116
	ds_write_b32 v3, v90 offset:2120
	ds_write_b32 v3, v91 offset:2124
	ds_write_b32 v3, v92 offset:3168
	ds_write_b32 v3, v93 offset:3172
	ds_write_b32 v3, v94 offset:3176
	ds_write_b32 v3, v95 offset:3180
	ds_write_b32 v3, v96 offset:4224
	ds_write_b32 v3, v97 offset:4228
	ds_write_b32 v3, v98 offset:4232
	ds_write_b32 v3, v99 offset:4236
	ds_write_b32 v3, v100 offset:5280
	ds_write_b32 v3, v101 offset:5284
	ds_write_b32 v3, v102 offset:5288
	ds_write_b32 v3, v103 offset:5292
	ds_write_b32 v3, v104 offset:6336
	ds_write_b32 v3, v105 offset:6340
	ds_write_b32 v3, v106 offset:6344
	ds_write_b32 v3, v107 offset:6348
	ds_write_b32 v3, v108 offset:7392
	ds_write_b32 v3, v109 offset:7396
	ds_write_b32 v3, v110 offset:7400
	ds_write_b32 v3, v111 offset:7404
	s_waitcnt lgkmcnt(0)
	s_mov_b32 s3, s0
	s_lshr_b32 s29, s3, 6
	s_and_b32 s35, s3, 63
	s_mul_i32 s58, s35, 0x30000
	s_lshl_b32 s59, s29, 7
	s_add_u32 s58, s58, s59
	s_add_u32 s58, s58, 0x1000
	s_add_u32 s48, s12, s58
	s_addc_u32 s49, s13, 0
	ds_read2_b32 v[8:9], v4 offset0:0 offset1:33
	ds_read2_b32 v[10:11], v4 offset0:66 offset1:99
	ds_read2_b32 v[12:13], v4 offset0:132 offset1:165
	ds_read2_b32 v[14:15], v4 offset0:198 offset1:231
	s_waitcnt lgkmcnt(0)
	v_cvt_pk_bf16_f32 v80, v8, v9
	v_cvt_pk_bf16_f32 v81, v10, v11
	v_cvt_pk_bf16_f32 v82, v12, v13
	v_cvt_pk_bf16_f32 v83, v14, v15
	global_store_dwordx4 v5, v[80:83], s[48:49]
	ds_read2_b32 v[8:9], v4 offset0:8 offset1:41
	ds_read2_b32 v[10:11], v4 offset0:74 offset1:107
	ds_read2_b32 v[12:13], v4 offset0:140 offset1:173
	ds_read2_b32 v[14:15], v4 offset0:206 offset1:239
	s_waitcnt lgkmcnt(0)
	v_cvt_pk_bf16_f32 v84, v8, v9
	v_cvt_pk_bf16_f32 v85, v10, v11
	v_cvt_pk_bf16_f32 v86, v12, v13
	v_cvt_pk_bf16_f32 v87, v14, v15
	v_add_u32_e32 v7, 0xc000, v5
	global_store_dwordx4 v7, v[84:87], s[48:49]
	ds_read2_b32 v[8:9], v4 offset0:16 offset1:49
	ds_read2_b32 v[10:11], v4 offset0:82 offset1:115
	ds_read2_b32 v[12:13], v4 offset0:148 offset1:181
	ds_read2_b32 v[14:15], v4 offset0:214 offset1:247
	s_waitcnt lgkmcnt(0)
	v_cvt_pk_bf16_f32 v88, v8, v9
	v_cvt_pk_bf16_f32 v89, v10, v11
	v_cvt_pk_bf16_f32 v90, v12, v13
	v_cvt_pk_bf16_f32 v91, v14, v15
	v_add_u32_e32 v7, 0x18000, v5
	global_store_dwordx4 v7, v[88:91], s[48:49]
	ds_read2_b32 v[8:9], v4 offset0:24 offset1:57
	ds_read2_b32 v[10:11], v4 offset0:90 offset1:123
	ds_read2_b32 v[12:13], v4 offset0:156 offset1:189
	ds_read2_b32 v[14:15], v4 offset0:222 offset1:255
	s_waitcnt lgkmcnt(0)
	v_cvt_pk_bf16_f32 v92, v8, v9
	v_cvt_pk_bf16_f32 v93, v10, v11
	v_cvt_pk_bf16_f32 v94, v12, v13
	v_cvt_pk_bf16_f32 v95, v14, v15
	v_add_u32_e32 v7, 0x24000, v5
	global_store_dwordx4 v7, v[92:95], s[48:49]
	s_mov_b32 s3, s0
	s_mul_i32 s29, s3, 0x1745e
	s_lshr_b32 s29, s29, 25
	s_mul_i32 s35, s29, 0x160
	s_sub_i32 s35, s3, s35
	s_mul_i32 s58, s29, 0x2c0000
	s_lshl_b32 s59, s35, 7
	s_add_u32 s58, s58, s59
	s_add_u32 s46, s10, s58
	s_addc_u32 s47, s11, 0
	global_load_dwordx4 v[80:83], v2, s[46:47] nt
	v_add_u32_e32 v7, 0x58000, v2
	global_load_dwordx4 v[84:87], v7, s[46:47] nt
	v_add_u32_e32 v7, 0xb0000, v2
	global_load_dwordx4 v[88:91], v7, s[46:47] nt
	v_add_u32_e32 v7, 0x108000, v2
	global_load_dwordx4 v[92:95], v7, s[46:47] nt
	v_add_u32_e32 v7, 0x160000, v2
	global_load_dwordx4 v[96:99], v7, s[46:47] nt
	v_add_u32_e32 v7, 0x1b8000, v2
	global_load_dwordx4 v[100:103], v7, s[46:47] nt
	v_add_u32_e32 v7, 0x210000, v2
	global_load_dwordx4 v[104:107], v7, s[46:47] nt
	v_add_u32_e32 v7, 0x268000, v2
	global_load_dwordx4 v[108:111], v7, s[46:47] nt
	s_waitcnt vmcnt(16)
	ds_write_b32 v3, v16
	ds_write_b32 v3, v17 offset:4
	ds_write_b32 v3, v18 offset:8
	ds_write_b32 v3, v19 offset:12
	ds_write_b32 v3, v20 offset:1056
	ds_write_b32 v3, v21 offset:1060
	ds_write_b32 v3, v22 offset:1064
	ds_write_b32 v3, v23 offset:1068
	ds_write_b32 v3, v24 offset:2112
	ds_write_b32 v3, v25 offset:2116
	ds_write_b32 v3, v26 offset:2120
	ds_write_b32 v3, v27 offset:2124
	ds_write_b32 v3, v28 offset:3168
	ds_write_b32 v3, v29 offset:3172
	ds_write_b32 v3, v30 offset:3176
	ds_write_b32 v3, v31 offset:3180
	ds_write_b32 v3, v32 offset:4224
	ds_write_b32 v3, v33 offset:4228
	ds_write_b32 v3, v34 offset:4232
	ds_write_b32 v3, v35 offset:4236
	ds_write_b32 v3, v36 offset:5280
	ds_write_b32 v3, v37 offset:5284
	ds_write_b32 v3, v38 offset:5288
	ds_write_b32 v3, v39 offset:5292
	ds_write_b32 v3, v40 offset:6336
	ds_write_b32 v3, v41 offset:6340
	ds_write_b32 v3, v42 offset:6344
	ds_write_b32 v3, v43 offset:6348
	ds_write_b32 v3, v44 offset:7392
	ds_write_b32 v3, v45 offset:7396
	ds_write_b32 v3, v46 offset:7400
	ds_write_b32 v3, v47 offset:7404
	s_waitcnt lgkmcnt(0)
	s_mov_b32 s3, s0
	s_lshr_b32 s29, s3, 6
	s_and_b32 s35, s3, 63
	s_lshl_b32 s58, s35, 17
	s_lshl_b32 s59, s29, 7
	s_add_u32 s58, s58, s59
	s_add_u32 s48, s30, s58
	s_addc_u32 s49, s31, 0
	ds_read2_b32 v[8:9], v4 offset0:0 offset1:33
	ds_read2_b32 v[10:11], v4 offset0:66 offset1:99
	ds_read2_b32 v[12:13], v4 offset0:132 offset1:165
	ds_read2_b32 v[14:15], v4 offset0:198 offset1:231
	s_waitcnt lgkmcnt(0)
	v_cvt_pk_bf16_f32 v16, v8, v9
	v_cvt_pk_bf16_f32 v17, v10, v11
	v_cvt_pk_bf16_f32 v18, v12, v13
	v_cvt_pk_bf16_f32 v19, v14, v15
	global_store_dwordx4 v6, v[16:19], s[48:49]
	ds_read2_b32 v[8:9], v4 offset0:8 offset1:41
	ds_read2_b32 v[10:11], v4 offset0:74 offset1:107
	ds_read2_b32 v[12:13], v4 offset0:140 offset1:173
	ds_read2_b32 v[14:15], v4 offset0:206 offset1:239
	s_waitcnt lgkmcnt(0)
	v_cvt_pk_bf16_f32 v20, v8, v9
	v_cvt_pk_bf16_f32 v21, v10, v11
	v_cvt_pk_bf16_f32 v22, v12, v13
	v_cvt_pk_bf16_f32 v23, v14, v15
	v_add_u32_e32 v7, 0x8000, v6
	global_store_dwordx4 v7, v[20:23], s[48:49]
	ds_read2_b32 v[8:9], v4 offset0:16 offset1:49
	ds_read2_b32 v[10:11], v4 offset0:82 offset1:115
	ds_read2_b32 v[12:13], v4 offset0:148 offset1:181
	ds_read2_b32 v[14:15], v4 offset0:214 offset1:247
	s_waitcnt lgkmcnt(0)
	v_cvt_pk_bf16_f32 v24, v8, v9
	v_cvt_pk_bf16_f32 v25, v10, v11
	v_cvt_pk_bf16_f32 v26, v12, v13
	v_cvt_pk_bf16_f32 v27, v14, v15
	v_add_u32_e32 v7, 0x10000, v6
	global_store_dwordx4 v7, v[24:27], s[48:49]
	ds_read2_b32 v[8:9], v4 offset0:24 offset1:57
	ds_read2_b32 v[10:11], v4 offset0:90 offset1:123
	ds_read2_b32 v[12:13], v4 offset0:156 offset1:189
	ds_read2_b32 v[14:15], v4 offset0:222 offset1:255
	s_waitcnt lgkmcnt(0)
	v_cvt_pk_bf16_f32 v28, v8, v9
	v_cvt_pk_bf16_f32 v29, v10, v11
	v_cvt_pk_bf16_f32 v30, v12, v13
	v_cvt_pk_bf16_f32 v31, v14, v15
	v_add_u32_e32 v7, 0x18000, v6
	global_store_dwordx4 v7, v[28:31], s[48:49]
	s_add_i32 s3, s0, 1024
	s_mul_i32 s29, s3, 0x1745e
	s_lshr_b32 s29, s29, 25
	s_mul_i32 s35, s29, 0x160
	s_sub_i32 s35, s3, s35
	s_mul_i32 s58, s29, 0x2c0000
	s_lshl_b32 s59, s35, 7
	s_add_u32 s58, s58, s59
	s_add_u32 s46, s10, s58
	s_addc_u32 s47, s11, 0
	global_load_dwordx4 v[16:19], v2, s[46:47] nt
	v_add_u32_e32 v7, 0x58000, v2
	global_load_dwordx4 v[20:23], v7, s[46:47] nt
	v_add_u32_e32 v7, 0xb0000, v2
	global_load_dwordx4 v[24:27], v7, s[46:47] nt
	v_add_u32_e32 v7, 0x108000, v2
	global_load_dwordx4 v[28:31], v7, s[46:47] nt
	v_add_u32_e32 v7, 0x160000, v2
	global_load_dwordx4 v[32:35], v7, s[46:47] nt
	v_add_u32_e32 v7, 0x1b8000, v2
	global_load_dwordx4 v[36:39], v7, s[46:47] nt
	v_add_u32_e32 v7, 0x210000, v2
	global_load_dwordx4 v[40:43], v7, s[46:47] nt
	v_add_u32_e32 v7, 0x268000, v2
	global_load_dwordx4 v[44:47], v7, s[46:47] nt
	s_waitcnt vmcnt(16)
	ds_write_b32 v3, v48
	ds_write_b32 v3, v49 offset:4
	ds_write_b32 v3, v50 offset:8
	ds_write_b32 v3, v51 offset:12
	ds_write_b32 v3, v52 offset:1056
	ds_write_b32 v3, v53 offset:1060
	ds_write_b32 v3, v54 offset:1064
	ds_write_b32 v3, v55 offset:1068
	ds_write_b32 v3, v56 offset:2112
	ds_write_b32 v3, v57 offset:2116
	ds_write_b32 v3, v58 offset:2120
	ds_write_b32 v3, v59 offset:2124
	ds_write_b32 v3, v60 offset:3168
	ds_write_b32 v3, v61 offset:3172
	ds_write_b32 v3, v62 offset:3176
	ds_write_b32 v3, v63 offset:3180
	ds_write_b32 v3, v64 offset:4224
	ds_write_b32 v3, v65 offset:4228
	ds_write_b32 v3, v66 offset:4232
	ds_write_b32 v3, v67 offset:4236
	ds_write_b32 v3, v68 offset:5280
	ds_write_b32 v3, v69 offset:5284
	ds_write_b32 v3, v70 offset:5288
	ds_write_b32 v3, v71 offset:5292
	ds_write_b32 v3, v72 offset:6336
	ds_write_b32 v3, v73 offset:6340
	ds_write_b32 v3, v74 offset:6344
	ds_write_b32 v3, v75 offset:6348
	ds_write_b32 v3, v76 offset:7392
	ds_write_b32 v3, v77 offset:7396
	ds_write_b32 v3, v78 offset:7400
	ds_write_b32 v3, v79 offset:7404
	s_waitcnt lgkmcnt(0)
	s_add_i32 s3, s0, 1024
	s_lshr_b32 s29, s3, 6
	s_and_b32 s35, s3, 63
	s_lshl_b32 s58, s35, 17
	s_lshl_b32 s59, s29, 7
	s_add_u32 s58, s58, s59
	s_add_u32 s48, s30, s58
	s_addc_u32 s49, s31, 0
	ds_read2_b32 v[8:9], v4 offset0:0 offset1:33
	ds_read2_b32 v[10:11], v4 offset0:66 offset1:99
	ds_read2_b32 v[12:13], v4 offset0:132 offset1:165
	ds_read2_b32 v[14:15], v4 offset0:198 offset1:231
	s_waitcnt lgkmcnt(0)
	v_cvt_pk_bf16_f32 v48, v8, v9
	v_cvt_pk_bf16_f32 v49, v10, v11
	v_cvt_pk_bf16_f32 v50, v12, v13
	v_cvt_pk_bf16_f32 v51, v14, v15
	global_store_dwordx4 v6, v[48:51], s[48:49]
	ds_read2_b32 v[8:9], v4 offset0:8 offset1:41
	ds_read2_b32 v[10:11], v4 offset0:74 offset1:107
	ds_read2_b32 v[12:13], v4 offset0:140 offset1:173
	ds_read2_b32 v[14:15], v4 offset0:206 offset1:239
	s_waitcnt lgkmcnt(0)
	v_cvt_pk_bf16_f32 v52, v8, v9
	v_cvt_pk_bf16_f32 v53, v10, v11
	v_cvt_pk_bf16_f32 v54, v12, v13
	v_cvt_pk_bf16_f32 v55, v14, v15
	v_add_u32_e32 v7, 0x8000, v6
	global_store_dwordx4 v7, v[52:55], s[48:49]
	ds_read2_b32 v[8:9], v4 offset0:16 offset1:49
	ds_read2_b32 v[10:11], v4 offset0:82 offset1:115
	ds_read2_b32 v[12:13], v4 offset0:148 offset1:181
	ds_read2_b32 v[14:15], v4 offset0:214 offset1:247
	s_waitcnt lgkmcnt(0)
	v_cvt_pk_bf16_f32 v56, v8, v9
	v_cvt_pk_bf16_f32 v57, v10, v11
	v_cvt_pk_bf16_f32 v58, v12, v13
	v_cvt_pk_bf16_f32 v59, v14, v15
	v_add_u32_e32 v7, 0x10000, v6
	global_store_dwordx4 v7, v[56:59], s[48:49]
	ds_read2_b32 v[8:9], v4 offset0:24 offset1:57
	ds_read2_b32 v[10:11], v4 offset0:90 offset1:123
	ds_read2_b32 v[12:13], v4 offset0:156 offset1:189
	ds_read2_b32 v[14:15], v4 offset0:222 offset1:255
	s_waitcnt lgkmcnt(0)
	v_cvt_pk_bf16_f32 v60, v8, v9
	v_cvt_pk_bf16_f32 v61, v10, v11
	v_cvt_pk_bf16_f32 v62, v12, v13
	v_cvt_pk_bf16_f32 v63, v14, v15
	v_add_u32_e32 v7, 0x18000, v6
	global_store_dwordx4 v7, v[60:63], s[48:49]
	s_add_i32 s3, s0, 2048
	s_mul_i32 s29, s3, 0x1745e
	s_lshr_b32 s29, s29, 25
	s_mul_i32 s35, s29, 0x160
	s_sub_i32 s35, s3, s35
	s_mul_i32 s58, s29, 0x2c0000
	s_lshl_b32 s59, s35, 7
	s_add_u32 s58, s58, s59
	s_add_u32 s46, s10, s58
	s_addc_u32 s47, s11, 0
	global_load_dwordx4 v[48:51], v2, s[46:47] nt
	v_add_u32_e32 v7, 0x58000, v2
	global_load_dwordx4 v[52:55], v7, s[46:47] nt
	v_add_u32_e32 v7, 0xb0000, v2
	global_load_dwordx4 v[56:59], v7, s[46:47] nt
	v_add_u32_e32 v7, 0x108000, v2
	global_load_dwordx4 v[60:63], v7, s[46:47] nt
	v_add_u32_e32 v7, 0x160000, v2
	global_load_dwordx4 v[64:67], v7, s[46:47] nt
	v_add_u32_e32 v7, 0x1b8000, v2
	global_load_dwordx4 v[68:71], v7, s[46:47] nt
	v_add_u32_e32 v7, 0x210000, v2
	global_load_dwordx4 v[72:75], v7, s[46:47] nt
	v_add_u32_e32 v7, 0x268000, v2
	global_load_dwordx4 v[76:79], v7, s[46:47] nt
	s_waitcnt vmcnt(16)
	ds_write_b32 v3, v80
	ds_write_b32 v3, v81 offset:4
	ds_write_b32 v3, v82 offset:8
	ds_write_b32 v3, v83 offset:12
	ds_write_b32 v3, v84 offset:1056
	ds_write_b32 v3, v85 offset:1060
	ds_write_b32 v3, v86 offset:1064
	ds_write_b32 v3, v87 offset:1068
	ds_write_b32 v3, v88 offset:2112
	ds_write_b32 v3, v89 offset:2116
	ds_write_b32 v3, v90 offset:2120
	ds_write_b32 v3, v91 offset:2124
	ds_write_b32 v3, v92 offset:3168
	ds_write_b32 v3, v93 offset:3172
	ds_write_b32 v3, v94 offset:3176
	ds_write_b32 v3, v95 offset:3180
	ds_write_b32 v3, v96 offset:4224
	ds_write_b32 v3, v97 offset:4228
	ds_write_b32 v3, v98 offset:4232
	ds_write_b32 v3, v99 offset:4236
	ds_write_b32 v3, v100 offset:5280
	ds_write_b32 v3, v101 offset:5284
	ds_write_b32 v3, v102 offset:5288
	ds_write_b32 v3, v103 offset:5292
	ds_write_b32 v3, v104 offset:6336
	ds_write_b32 v3, v105 offset:6340
	ds_write_b32 v3, v106 offset:6344
	ds_write_b32 v3, v107 offset:6348
	ds_write_b32 v3, v108 offset:7392
	ds_write_b32 v3, v109 offset:7396
	ds_write_b32 v3, v110 offset:7400
	ds_write_b32 v3, v111 offset:7404
	s_waitcnt lgkmcnt(0)
	s_mov_b32 s3, s0
	s_mul_i32 s29, s3, 0x1745e
	s_lshr_b32 s29, s29, 25
	s_mul_i32 s35, s29, 0x160
	s_sub_i32 s35, s3, s35
	s_lshl_b32 s58, s35, 17
	s_lshl_b32 s59, s29, 7
	s_add_u32 s58, s58, s59
	s_add_u32 s48, s42, s58
	s_addc_u32 s49, s43, 0
	ds_read2_b32 v[8:9], v4 offset0:0 offset1:33
	ds_read2_b32 v[10:11], v4 offset0:66 offset1:99
	ds_read2_b32 v[12:13], v4 offset0:132 offset1:165
	ds_read2_b32 v[14:15], v4 offset0:198 offset1:231
	s_waitcnt lgkmcnt(0)
	v_cvt_pk_bf16_f32 v80, v8, v9
	v_cvt_pk_bf16_f32 v81, v10, v11
	v_cvt_pk_bf16_f32 v82, v12, v13
	v_cvt_pk_bf16_f32 v83, v14, v15
	global_store_dwordx4 v6, v[80:83], s[48:49]
	ds_read2_b32 v[8:9], v4 offset0:8 offset1:41
	ds_read2_b32 v[10:11], v4 offset0:74 offset1:107
	ds_read2_b32 v[12:13], v4 offset0:140 offset1:173
	ds_read2_b32 v[14:15], v4 offset0:206 offset1:239
	s_waitcnt lgkmcnt(0)
	v_cvt_pk_bf16_f32 v84, v8, v9
	v_cvt_pk_bf16_f32 v85, v10, v11
	v_cvt_pk_bf16_f32 v86, v12, v13
	v_cvt_pk_bf16_f32 v87, v14, v15
	v_add_u32_e32 v7, 0x8000, v6
	global_store_dwordx4 v7, v[84:87], s[48:49]
	ds_read2_b32 v[8:9], v4 offset0:16 offset1:49
	ds_read2_b32 v[10:11], v4 offset0:82 offset1:115
	ds_read2_b32 v[12:13], v4 offset0:148 offset1:181
	ds_read2_b32 v[14:15], v4 offset0:214 offset1:247
	s_waitcnt lgkmcnt(0)
	v_cvt_pk_bf16_f32 v88, v8, v9
	v_cvt_pk_bf16_f32 v89, v10, v11
	v_cvt_pk_bf16_f32 v90, v12, v13
	v_cvt_pk_bf16_f32 v91, v14, v15
	v_add_u32_e32 v7, 0x10000, v6
	global_store_dwordx4 v7, v[88:91], s[48:49]
	ds_read2_b32 v[8:9], v4 offset0:24 offset1:57
	ds_read2_b32 v[10:11], v4 offset0:90 offset1:123
	ds_read2_b32 v[12:13], v4 offset0:156 offset1:189
	ds_read2_b32 v[14:15], v4 offset0:222 offset1:255
	s_waitcnt lgkmcnt(0)
	v_cvt_pk_bf16_f32 v92, v8, v9
	v_cvt_pk_bf16_f32 v93, v10, v11
	v_cvt_pk_bf16_f32 v94, v12, v13
	v_cvt_pk_bf16_f32 v95, v14, v15
	v_add_u32_e32 v7, 0x18000, v6
	global_store_dwordx4 v7, v[92:95], s[48:49]
	s_add_i32 s3, s0, 3072
	s_mul_i32 s29, s3, 0x1745e
	s_lshr_b32 s29, s29, 25
	s_mul_i32 s35, s29, 0x160
	s_sub_i32 s35, s3, s35
	s_mul_i32 s58, s29, 0x2c0000
	s_lshl_b32 s59, s35, 7
	s_add_u32 s58, s58, s59
	s_add_u32 s46, s10, s58
	s_addc_u32 s47, s11, 0
	global_load_dwordx4 v[80:83], v2, s[46:47] nt
	v_add_u32_e32 v7, 0x58000, v2
	global_load_dwordx4 v[84:87], v7, s[46:47] nt
	v_add_u32_e32 v7, 0xb0000, v2
	global_load_dwordx4 v[88:91], v7, s[46:47] nt
	v_add_u32_e32 v7, 0x108000, v2
	global_load_dwordx4 v[92:95], v7, s[46:47] nt
	v_add_u32_e32 v7, 0x160000, v2
	global_load_dwordx4 v[96:99], v7, s[46:47] nt
	v_add_u32_e32 v7, 0x1b8000, v2
	global_load_dwordx4 v[100:103], v7, s[46:47] nt
	v_add_u32_e32 v7, 0x210000, v2
	global_load_dwordx4 v[104:107], v7, s[46:47] nt
	v_add_u32_e32 v7, 0x268000, v2
	global_load_dwordx4 v[108:111], v7, s[46:47] nt
	s_waitcnt vmcnt(16)
	ds_write_b32 v3, v16
	ds_write_b32 v3, v17 offset:4
	ds_write_b32 v3, v18 offset:8
	ds_write_b32 v3, v19 offset:12
	ds_write_b32 v3, v20 offset:1056
	ds_write_b32 v3, v21 offset:1060
	ds_write_b32 v3, v22 offset:1064
	ds_write_b32 v3, v23 offset:1068
	ds_write_b32 v3, v24 offset:2112
	ds_write_b32 v3, v25 offset:2116
	ds_write_b32 v3, v26 offset:2120
	ds_write_b32 v3, v27 offset:2124
	ds_write_b32 v3, v28 offset:3168
	ds_write_b32 v3, v29 offset:3172
	ds_write_b32 v3, v30 offset:3176
	ds_write_b32 v3, v31 offset:3180
	ds_write_b32 v3, v32 offset:4224
	ds_write_b32 v3, v33 offset:4228
	ds_write_b32 v3, v34 offset:4232
	ds_write_b32 v3, v35 offset:4236
	ds_write_b32 v3, v36 offset:5280
	ds_write_b32 v3, v37 offset:5284
	ds_write_b32 v3, v38 offset:5288
	ds_write_b32 v3, v39 offset:5292
	ds_write_b32 v3, v40 offset:6336
	ds_write_b32 v3, v41 offset:6340
	ds_write_b32 v3, v42 offset:6344
	ds_write_b32 v3, v43 offset:6348
	ds_write_b32 v3, v44 offset:7392
	ds_write_b32 v3, v45 offset:7396
	ds_write_b32 v3, v46 offset:7400
	ds_write_b32 v3, v47 offset:7404
	s_waitcnt lgkmcnt(0)
	s_add_i32 s3, s0, 1024
	s_mul_i32 s29, s3, 0x1745e
	s_lshr_b32 s29, s29, 25
	s_mul_i32 s35, s29, 0x160
	s_sub_i32 s35, s3, s35
	s_lshl_b32 s58, s35, 17
	s_lshl_b32 s59, s29, 7
	s_add_u32 s58, s58, s59
	s_add_u32 s48, s42, s58
	s_addc_u32 s49, s43, 0
	ds_read2_b32 v[8:9], v4 offset0:0 offset1:33
	ds_read2_b32 v[10:11], v4 offset0:66 offset1:99
	ds_read2_b32 v[12:13], v4 offset0:132 offset1:165
	ds_read2_b32 v[14:15], v4 offset0:198 offset1:231
	s_waitcnt lgkmcnt(0)
	v_cvt_pk_bf16_f32 v16, v8, v9
	v_cvt_pk_bf16_f32 v17, v10, v11
	v_cvt_pk_bf16_f32 v18, v12, v13
	v_cvt_pk_bf16_f32 v19, v14, v15
	global_store_dwordx4 v6, v[16:19], s[48:49]
	ds_read2_b32 v[8:9], v4 offset0:8 offset1:41
	ds_read2_b32 v[10:11], v4 offset0:74 offset1:107
	ds_read2_b32 v[12:13], v4 offset0:140 offset1:173
	ds_read2_b32 v[14:15], v4 offset0:206 offset1:239
	s_waitcnt lgkmcnt(0)
	v_cvt_pk_bf16_f32 v20, v8, v9
	v_cvt_pk_bf16_f32 v21, v10, v11
	v_cvt_pk_bf16_f32 v22, v12, v13
	v_cvt_pk_bf16_f32 v23, v14, v15
	v_add_u32_e32 v7, 0x8000, v6
	global_store_dwordx4 v7, v[20:23], s[48:49]
	ds_read2_b32 v[8:9], v4 offset0:16 offset1:49
	ds_read2_b32 v[10:11], v4 offset0:82 offset1:115
	ds_read2_b32 v[12:13], v4 offset0:148 offset1:181
	ds_read2_b32 v[14:15], v4 offset0:214 offset1:247
	s_waitcnt lgkmcnt(0)
	v_cvt_pk_bf16_f32 v24, v8, v9
	v_cvt_pk_bf16_f32 v25, v10, v11
	v_cvt_pk_bf16_f32 v26, v12, v13
	v_cvt_pk_bf16_f32 v27, v14, v15
	v_add_u32_e32 v7, 0x10000, v6
	global_store_dwordx4 v7, v[24:27], s[48:49]
	ds_read2_b32 v[8:9], v4 offset0:24 offset1:57
	ds_read2_b32 v[10:11], v4 offset0:90 offset1:123
	ds_read2_b32 v[12:13], v4 offset0:156 offset1:189
	ds_read2_b32 v[14:15], v4 offset0:222 offset1:255
	s_waitcnt lgkmcnt(0)
	v_cvt_pk_bf16_f32 v28, v8, v9
	v_cvt_pk_bf16_f32 v29, v10, v11
	v_cvt_pk_bf16_f32 v30, v12, v13
	v_cvt_pk_bf16_f32 v31, v14, v15
	v_add_u32_e32 v7, 0x18000, v6
	global_store_dwordx4 v7, v[28:31], s[48:49]
	s_add_i32 s3, s0, 4096
	s_mul_i32 s29, s3, 0x1745e
	s_lshr_b32 s29, s29, 25
	s_mul_i32 s35, s29, 0x160
	s_sub_i32 s35, s3, s35
	s_mul_i32 s58, s29, 0x2c0000
	s_lshl_b32 s59, s35, 7
	s_add_u32 s58, s58, s59
	s_add_u32 s46, s10, s58
	s_addc_u32 s47, s11, 0
	global_load_dwordx4 v[16:19], v2, s[46:47] nt
	v_add_u32_e32 v7, 0x58000, v2
	global_load_dwordx4 v[20:23], v7, s[46:47] nt
	v_add_u32_e32 v7, 0xb0000, v2
	global_load_dwordx4 v[24:27], v7, s[46:47] nt
	v_add_u32_e32 v7, 0x108000, v2
	global_load_dwordx4 v[28:31], v7, s[46:47] nt
	v_add_u32_e32 v7, 0x160000, v2
	global_load_dwordx4 v[32:35], v7, s[46:47] nt
	v_add_u32_e32 v7, 0x1b8000, v2
	global_load_dwordx4 v[36:39], v7, s[46:47] nt
	v_add_u32_e32 v7, 0x210000, v2
	global_load_dwordx4 v[40:43], v7, s[46:47] nt
	v_add_u32_e32 v7, 0x268000, v2
	global_load_dwordx4 v[44:47], v7, s[46:47] nt
	s_waitcnt vmcnt(16)
	ds_write_b32 v3, v48
	ds_write_b32 v3, v49 offset:4
	ds_write_b32 v3, v50 offset:8
	ds_write_b32 v3, v51 offset:12
	ds_write_b32 v3, v52 offset:1056
	ds_write_b32 v3, v53 offset:1060
	ds_write_b32 v3, v54 offset:1064
	ds_write_b32 v3, v55 offset:1068
	ds_write_b32 v3, v56 offset:2112
	ds_write_b32 v3, v57 offset:2116
	ds_write_b32 v3, v58 offset:2120
	ds_write_b32 v3, v59 offset:2124
	ds_write_b32 v3, v60 offset:3168
	ds_write_b32 v3, v61 offset:3172
	ds_write_b32 v3, v62 offset:3176
	ds_write_b32 v3, v63 offset:3180
	ds_write_b32 v3, v64 offset:4224
	ds_write_b32 v3, v65 offset:4228
	ds_write_b32 v3, v66 offset:4232
	ds_write_b32 v3, v67 offset:4236
	ds_write_b32 v3, v68 offset:5280
	ds_write_b32 v3, v69 offset:5284
	ds_write_b32 v3, v70 offset:5288
	ds_write_b32 v3, v71 offset:5292
	ds_write_b32 v3, v72 offset:6336
	ds_write_b32 v3, v73 offset:6340
	ds_write_b32 v3, v74 offset:6344
	ds_write_b32 v3, v75 offset:6348
	ds_write_b32 v3, v76 offset:7392
	ds_write_b32 v3, v77 offset:7396
	ds_write_b32 v3, v78 offset:7400
	ds_write_b32 v3, v79 offset:7404
	s_waitcnt lgkmcnt(0)
	s_add_i32 s3, s0, 2048
	s_mul_i32 s29, s3, 0x1745e
	s_lshr_b32 s29, s29, 25
	s_mul_i32 s35, s29, 0x160
	s_sub_i32 s35, s3, s35
	s_lshl_b32 s58, s35, 17
	s_lshl_b32 s59, s29, 7
	s_add_u32 s58, s58, s59
	s_add_u32 s48, s42, s58
	s_addc_u32 s49, s43, 0
	ds_read2_b32 v[8:9], v4 offset0:0 offset1:33
	ds_read2_b32 v[10:11], v4 offset0:66 offset1:99
	ds_read2_b32 v[12:13], v4 offset0:132 offset1:165
	ds_read2_b32 v[14:15], v4 offset0:198 offset1:231
	s_waitcnt lgkmcnt(0)
	v_cvt_pk_bf16_f32 v48, v8, v9
	v_cvt_pk_bf16_f32 v49, v10, v11
	v_cvt_pk_bf16_f32 v50, v12, v13
	v_cvt_pk_bf16_f32 v51, v14, v15
	global_store_dwordx4 v6, v[48:51], s[48:49]
	ds_read2_b32 v[8:9], v4 offset0:8 offset1:41
	ds_read2_b32 v[10:11], v4 offset0:74 offset1:107
	ds_read2_b32 v[12:13], v4 offset0:140 offset1:173
	ds_read2_b32 v[14:15], v4 offset0:206 offset1:239
	s_waitcnt lgkmcnt(0)
	v_cvt_pk_bf16_f32 v52, v8, v9
	v_cvt_pk_bf16_f32 v53, v10, v11
	v_cvt_pk_bf16_f32 v54, v12, v13
	v_cvt_pk_bf16_f32 v55, v14, v15
	v_add_u32_e32 v7, 0x8000, v6
	global_store_dwordx4 v7, v[52:55], s[48:49]
	ds_read2_b32 v[8:9], v4 offset0:16 offset1:49
	ds_read2_b32 v[10:11], v4 offset0:82 offset1:115
	ds_read2_b32 v[12:13], v4 offset0:148 offset1:181
	ds_read2_b32 v[14:15], v4 offset0:214 offset1:247
	s_waitcnt lgkmcnt(0)
	v_cvt_pk_bf16_f32 v56, v8, v9
	v_cvt_pk_bf16_f32 v57, v10, v11
	v_cvt_pk_bf16_f32 v58, v12, v13
	v_cvt_pk_bf16_f32 v59, v14, v15
	v_add_u32_e32 v7, 0x10000, v6
	global_store_dwordx4 v7, v[56:59], s[48:49]
	ds_read2_b32 v[8:9], v4 offset0:24 offset1:57
	ds_read2_b32 v[10:11], v4 offset0:90 offset1:123
	ds_read2_b32 v[12:13], v4 offset0:156 offset1:189
	ds_read2_b32 v[14:15], v4 offset0:222 offset1:255
	s_waitcnt lgkmcnt(0)
	v_cvt_pk_bf16_f32 v60, v8, v9
	v_cvt_pk_bf16_f32 v61, v10, v11
	v_cvt_pk_bf16_f32 v62, v12, v13
	v_cvt_pk_bf16_f32 v63, v14, v15
	v_add_u32_e32 v7, 0x18000, v6
	global_store_dwordx4 v7, v[60:63], s[48:49]
	s_add_i32 s3, s0, 5120
	s_mul_i32 s29, s3, 0x1745e
	s_lshr_b32 s29, s29, 25
	s_mul_i32 s35, s29, 0x160
	s_sub_i32 s35, s3, s35
	s_mul_i32 s58, s29, 0x2c0000
	s_lshl_b32 s59, s35, 7
	s_add_u32 s58, s58, s59
	s_add_u32 s46, s10, s58
	s_addc_u32 s47, s11, 0
	global_load_dwordx4 v[48:51], v2, s[46:47] nt
	v_add_u32_e32 v7, 0x58000, v2
	global_load_dwordx4 v[52:55], v7, s[46:47] nt
	v_add_u32_e32 v7, 0xb0000, v2
	global_load_dwordx4 v[56:59], v7, s[46:47] nt
	v_add_u32_e32 v7, 0x108000, v2
	global_load_dwordx4 v[60:63], v7, s[46:47] nt
	v_add_u32_e32 v7, 0x160000, v2
	global_load_dwordx4 v[64:67], v7, s[46:47] nt
	v_add_u32_e32 v7, 0x1b8000, v2
	global_load_dwordx4 v[68:71], v7, s[46:47] nt
	v_add_u32_e32 v7, 0x210000, v2
	global_load_dwordx4 v[72:75], v7, s[46:47] nt
	v_add_u32_e32 v7, 0x268000, v2
	global_load_dwordx4 v[76:79], v7, s[46:47] nt
	s_waitcnt vmcnt(16)
	ds_write_b32 v3, v80
	ds_write_b32 v3, v81 offset:4
	ds_write_b32 v3, v82 offset:8
	ds_write_b32 v3, v83 offset:12
	ds_write_b32 v3, v84 offset:1056
	ds_write_b32 v3, v85 offset:1060
	ds_write_b32 v3, v86 offset:1064
	ds_write_b32 v3, v87 offset:1068
	ds_write_b32 v3, v88 offset:2112
	ds_write_b32 v3, v89 offset:2116
	ds_write_b32 v3, v90 offset:2120
	ds_write_b32 v3, v91 offset:2124
	ds_write_b32 v3, v92 offset:3168
	ds_write_b32 v3, v93 offset:3172
	ds_write_b32 v3, v94 offset:3176
	ds_write_b32 v3, v95 offset:3180
	ds_write_b32 v3, v96 offset:4224
	ds_write_b32 v3, v97 offset:4228
	ds_write_b32 v3, v98 offset:4232
	ds_write_b32 v3, v99 offset:4236
	ds_write_b32 v3, v100 offset:5280
	ds_write_b32 v3, v101 offset:5284
	ds_write_b32 v3, v102 offset:5288
	ds_write_b32 v3, v103 offset:5292
	ds_write_b32 v3, v104 offset:6336
	ds_write_b32 v3, v105 offset:6340
	ds_write_b32 v3, v106 offset:6344
	ds_write_b32 v3, v107 offset:6348
	ds_write_b32 v3, v108 offset:7392
	ds_write_b32 v3, v109 offset:7396
	ds_write_b32 v3, v110 offset:7400
	ds_write_b32 v3, v111 offset:7404
	s_waitcnt lgkmcnt(0)
	s_add_i32 s3, s0, 3072
	s_mul_i32 s29, s3, 0x1745e
	s_lshr_b32 s29, s29, 25
	s_mul_i32 s35, s29, 0x160
	s_sub_i32 s35, s3, s35
	s_lshl_b32 s58, s35, 17
	s_lshl_b32 s59, s29, 7
	s_add_u32 s58, s58, s59
	s_add_u32 s48, s42, s58
	s_addc_u32 s49, s43, 0
	ds_read2_b32 v[8:9], v4 offset0:0 offset1:33
	ds_read2_b32 v[10:11], v4 offset0:66 offset1:99
	ds_read2_b32 v[12:13], v4 offset0:132 offset1:165
	ds_read2_b32 v[14:15], v4 offset0:198 offset1:231
	s_waitcnt lgkmcnt(0)
	v_cvt_pk_bf16_f32 v80, v8, v9
	v_cvt_pk_bf16_f32 v81, v10, v11
	v_cvt_pk_bf16_f32 v82, v12, v13
	v_cvt_pk_bf16_f32 v83, v14, v15
	global_store_dwordx4 v6, v[80:83], s[48:49]
	ds_read2_b32 v[8:9], v4 offset0:8 offset1:41
	ds_read2_b32 v[10:11], v4 offset0:74 offset1:107
	ds_read2_b32 v[12:13], v4 offset0:140 offset1:173
	ds_read2_b32 v[14:15], v4 offset0:206 offset1:239
	s_waitcnt lgkmcnt(0)
	v_cvt_pk_bf16_f32 v84, v8, v9
	v_cvt_pk_bf16_f32 v85, v10, v11
	v_cvt_pk_bf16_f32 v86, v12, v13
	v_cvt_pk_bf16_f32 v87, v14, v15
	v_add_u32_e32 v7, 0x8000, v6
	global_store_dwordx4 v7, v[84:87], s[48:49]
	ds_read2_b32 v[8:9], v4 offset0:16 offset1:49
	ds_read2_b32 v[10:11], v4 offset0:82 offset1:115
	ds_read2_b32 v[12:13], v4 offset0:148 offset1:181
	ds_read2_b32 v[14:15], v4 offset0:214 offset1:247
	s_waitcnt lgkmcnt(0)
	v_cvt_pk_bf16_f32 v88, v8, v9
	v_cvt_pk_bf16_f32 v89, v10, v11
	v_cvt_pk_bf16_f32 v90, v12, v13
	v_cvt_pk_bf16_f32 v91, v14, v15
	v_add_u32_e32 v7, 0x10000, v6
	global_store_dwordx4 v7, v[88:91], s[48:49]
	ds_read2_b32 v[8:9], v4 offset0:24 offset1:57
	ds_read2_b32 v[10:11], v4 offset0:90 offset1:123
	ds_read2_b32 v[12:13], v4 offset0:156 offset1:189
	ds_read2_b32 v[14:15], v4 offset0:222 offset1:255
	s_waitcnt lgkmcnt(0)
	v_cvt_pk_bf16_f32 v92, v8, v9
	v_cvt_pk_bf16_f32 v93, v10, v11
	v_cvt_pk_bf16_f32 v94, v12, v13
	v_cvt_pk_bf16_f32 v95, v14, v15
	v_add_u32_e32 v7, 0x18000, v6
	global_store_dwordx4 v7, v[92:95], s[48:49]
	s_add_i32 s3, s0, 6144
	s_mul_i32 s29, s3, 0x1745e
	s_lshr_b32 s29, s29, 25
	s_mul_i32 s35, s29, 0x160
	s_sub_i32 s35, s3, s35
	s_mul_i32 s58, s29, 0x2c0000
	s_lshl_b32 s59, s35, 7
	s_add_u32 s58, s58, s59
	s_add_u32 s46, s10, s58
	s_addc_u32 s47, s11, 0
	global_load_dwordx4 v[80:83], v2, s[46:47] nt
	v_add_u32_e32 v7, 0x58000, v2
	global_load_dwordx4 v[84:87], v7, s[46:47] nt
	v_add_u32_e32 v7, 0xb0000, v2
	global_load_dwordx4 v[88:91], v7, s[46:47] nt
	v_add_u32_e32 v7, 0x108000, v2
	global_load_dwordx4 v[92:95], v7, s[46:47] nt
	v_add_u32_e32 v7, 0x160000, v2
	global_load_dwordx4 v[96:99], v7, s[46:47] nt
	v_add_u32_e32 v7, 0x1b8000, v2
	global_load_dwordx4 v[100:103], v7, s[46:47] nt
	v_add_u32_e32 v7, 0x210000, v2
	global_load_dwordx4 v[104:107], v7, s[46:47] nt
	v_add_u32_e32 v7, 0x268000, v2
	global_load_dwordx4 v[108:111], v7, s[46:47] nt
	s_waitcnt vmcnt(16)
	ds_write_b32 v3, v16
	ds_write_b32 v3, v17 offset:4
	ds_write_b32 v3, v18 offset:8
	ds_write_b32 v3, v19 offset:12
	ds_write_b32 v3, v20 offset:1056
	ds_write_b32 v3, v21 offset:1060
	ds_write_b32 v3, v22 offset:1064
	ds_write_b32 v3, v23 offset:1068
	ds_write_b32 v3, v24 offset:2112
	ds_write_b32 v3, v25 offset:2116
	ds_write_b32 v3, v26 offset:2120
	ds_write_b32 v3, v27 offset:2124
	ds_write_b32 v3, v28 offset:3168
	ds_write_b32 v3, v29 offset:3172
	ds_write_b32 v3, v30 offset:3176
	ds_write_b32 v3, v31 offset:3180
	ds_write_b32 v3, v32 offset:4224
	ds_write_b32 v3, v33 offset:4228
	ds_write_b32 v3, v34 offset:4232
	ds_write_b32 v3, v35 offset:4236
	ds_write_b32 v3, v36 offset:5280
	ds_write_b32 v3, v37 offset:5284
	ds_write_b32 v3, v38 offset:5288
	ds_write_b32 v3, v39 offset:5292
	ds_write_b32 v3, v40 offset:6336
	ds_write_b32 v3, v41 offset:6340
	ds_write_b32 v3, v42 offset:6344
	ds_write_b32 v3, v43 offset:6348
	ds_write_b32 v3, v44 offset:7392
	ds_write_b32 v3, v45 offset:7396
	ds_write_b32 v3, v46 offset:7400
	ds_write_b32 v3, v47 offset:7404
	s_waitcnt lgkmcnt(0)
	s_add_i32 s3, s0, 4096
	s_mul_i32 s29, s3, 0x1745e
	s_lshr_b32 s29, s29, 25
	s_mul_i32 s35, s29, 0x160
	s_sub_i32 s35, s3, s35
	s_lshl_b32 s58, s35, 17
	s_lshl_b32 s59, s29, 7
	s_add_u32 s58, s58, s59
	s_add_u32 s48, s42, s58
	s_addc_u32 s49, s43, 0
	ds_read2_b32 v[8:9], v4 offset0:0 offset1:33
	ds_read2_b32 v[10:11], v4 offset0:66 offset1:99
	ds_read2_b32 v[12:13], v4 offset0:132 offset1:165
	ds_read2_b32 v[14:15], v4 offset0:198 offset1:231
	s_waitcnt lgkmcnt(0)
	v_cvt_pk_bf16_f32 v16, v8, v9
	v_cvt_pk_bf16_f32 v17, v10, v11
	v_cvt_pk_bf16_f32 v18, v12, v13
	v_cvt_pk_bf16_f32 v19, v14, v15
	global_store_dwordx4 v6, v[16:19], s[48:49]
	ds_read2_b32 v[8:9], v4 offset0:8 offset1:41
	ds_read2_b32 v[10:11], v4 offset0:74 offset1:107
	ds_read2_b32 v[12:13], v4 offset0:140 offset1:173
	ds_read2_b32 v[14:15], v4 offset0:206 offset1:239
	s_waitcnt lgkmcnt(0)
	v_cvt_pk_bf16_f32 v20, v8, v9
	v_cvt_pk_bf16_f32 v21, v10, v11
	v_cvt_pk_bf16_f32 v22, v12, v13
	v_cvt_pk_bf16_f32 v23, v14, v15
	v_add_u32_e32 v7, 0x8000, v6
	global_store_dwordx4 v7, v[20:23], s[48:49]
	ds_read2_b32 v[8:9], v4 offset0:16 offset1:49
	ds_read2_b32 v[10:11], v4 offset0:82 offset1:115
	ds_read2_b32 v[12:13], v4 offset0:148 offset1:181
	ds_read2_b32 v[14:15], v4 offset0:214 offset1:247
	s_waitcnt lgkmcnt(0)
	v_cvt_pk_bf16_f32 v24, v8, v9
	v_cvt_pk_bf16_f32 v25, v10, v11
	v_cvt_pk_bf16_f32 v26, v12, v13
	v_cvt_pk_bf16_f32 v27, v14, v15
	v_add_u32_e32 v7, 0x10000, v6
	global_store_dwordx4 v7, v[24:27], s[48:49]
	ds_read2_b32 v[8:9], v4 offset0:24 offset1:57
	ds_read2_b32 v[10:11], v4 offset0:90 offset1:123
	ds_read2_b32 v[12:13], v4 offset0:156 offset1:189
	ds_read2_b32 v[14:15], v4 offset0:222 offset1:255
	s_waitcnt lgkmcnt(0)
	v_cvt_pk_bf16_f32 v28, v8, v9
	v_cvt_pk_bf16_f32 v29, v10, v11
	v_cvt_pk_bf16_f32 v30, v12, v13
	v_cvt_pk_bf16_f32 v31, v14, v15
	v_add_u32_e32 v7, 0x18000, v6
	global_store_dwordx4 v7, v[28:31], s[48:49]
	s_add_i32 s3, s0, 7168
	s_mul_i32 s29, s3, 0x1745e
	s_lshr_b32 s29, s29, 25
	s_mul_i32 s35, s29, 0x160
	s_sub_i32 s35, s3, s35
	s_mul_i32 s58, s29, 0x2c0000
	s_lshl_b32 s59, s35, 7
	s_add_u32 s58, s58, s59
	s_add_u32 s46, s10, s58
	s_addc_u32 s47, s11, 0
	global_load_dwordx4 v[16:19], v2, s[46:47] nt
	v_add_u32_e32 v7, 0x58000, v2
	global_load_dwordx4 v[20:23], v7, s[46:47] nt
	v_add_u32_e32 v7, 0xb0000, v2
	global_load_dwordx4 v[24:27], v7, s[46:47] nt
	v_add_u32_e32 v7, 0x108000, v2
	global_load_dwordx4 v[28:31], v7, s[46:47] nt
	v_add_u32_e32 v7, 0x160000, v2
	global_load_dwordx4 v[32:35], v7, s[46:47] nt
	v_add_u32_e32 v7, 0x1b8000, v2
	global_load_dwordx4 v[36:39], v7, s[46:47] nt
	v_add_u32_e32 v7, 0x210000, v2
	global_load_dwordx4 v[40:43], v7, s[46:47] nt
	v_add_u32_e32 v7, 0x268000, v2
	global_load_dwordx4 v[44:47], v7, s[46:47] nt
	s_waitcnt vmcnt(16)
	ds_write_b32 v3, v48
	ds_write_b32 v3, v49 offset:4
	ds_write_b32 v3, v50 offset:8
	ds_write_b32 v3, v51 offset:12
	ds_write_b32 v3, v52 offset:1056
	ds_write_b32 v3, v53 offset:1060
	ds_write_b32 v3, v54 offset:1064
	ds_write_b32 v3, v55 offset:1068
	ds_write_b32 v3, v56 offset:2112
	ds_write_b32 v3, v57 offset:2116
	ds_write_b32 v3, v58 offset:2120
	ds_write_b32 v3, v59 offset:2124
	ds_write_b32 v3, v60 offset:3168
	ds_write_b32 v3, v61 offset:3172
	ds_write_b32 v3, v62 offset:3176
	ds_write_b32 v3, v63 offset:3180
	ds_write_b32 v3, v64 offset:4224
	ds_write_b32 v3, v65 offset:4228
	ds_write_b32 v3, v66 offset:4232
	ds_write_b32 v3, v67 offset:4236
	ds_write_b32 v3, v68 offset:5280
	ds_write_b32 v3, v69 offset:5284
	ds_write_b32 v3, v70 offset:5288
	ds_write_b32 v3, v71 offset:5292
	ds_write_b32 v3, v72 offset:6336
	ds_write_b32 v3, v73 offset:6340
	ds_write_b32 v3, v74 offset:6344
	ds_write_b32 v3, v75 offset:6348
	ds_write_b32 v3, v76 offset:7392
	ds_write_b32 v3, v77 offset:7396
	ds_write_b32 v3, v78 offset:7400
	ds_write_b32 v3, v79 offset:7404
	s_waitcnt lgkmcnt(0)
	s_add_i32 s3, s0, 5120
	s_mul_i32 s29, s3, 0x1745e
	s_lshr_b32 s29, s29, 25
	s_mul_i32 s35, s29, 0x160
	s_sub_i32 s35, s3, s35
	s_lshl_b32 s58, s35, 17
	s_lshl_b32 s59, s29, 7
	s_add_u32 s58, s58, s59
	s_add_u32 s48, s42, s58
	s_addc_u32 s49, s43, 0
	ds_read2_b32 v[8:9], v4 offset0:0 offset1:33
	ds_read2_b32 v[10:11], v4 offset0:66 offset1:99
	ds_read2_b32 v[12:13], v4 offset0:132 offset1:165
	ds_read2_b32 v[14:15], v4 offset0:198 offset1:231
	s_waitcnt lgkmcnt(0)
	v_cvt_pk_bf16_f32 v48, v8, v9
	v_cvt_pk_bf16_f32 v49, v10, v11
	v_cvt_pk_bf16_f32 v50, v12, v13
	v_cvt_pk_bf16_f32 v51, v14, v15
	global_store_dwordx4 v6, v[48:51], s[48:49]
	ds_read2_b32 v[8:9], v4 offset0:8 offset1:41
	ds_read2_b32 v[10:11], v4 offset0:74 offset1:107
	ds_read2_b32 v[12:13], v4 offset0:140 offset1:173
	ds_read2_b32 v[14:15], v4 offset0:206 offset1:239
	s_waitcnt lgkmcnt(0)
	v_cvt_pk_bf16_f32 v52, v8, v9
	v_cvt_pk_bf16_f32 v53, v10, v11
	v_cvt_pk_bf16_f32 v54, v12, v13
	v_cvt_pk_bf16_f32 v55, v14, v15
	v_add_u32_e32 v7, 0x8000, v6
	global_store_dwordx4 v7, v[52:55], s[48:49]
	ds_read2_b32 v[8:9], v4 offset0:16 offset1:49
	ds_read2_b32 v[10:11], v4 offset0:82 offset1:115
	ds_read2_b32 v[12:13], v4 offset0:148 offset1:181
	ds_read2_b32 v[14:15], v4 offset0:214 offset1:247
	s_waitcnt lgkmcnt(0)
	v_cvt_pk_bf16_f32 v56, v8, v9
	v_cvt_pk_bf16_f32 v57, v10, v11
	v_cvt_pk_bf16_f32 v58, v12, v13
	v_cvt_pk_bf16_f32 v59, v14, v15
	v_add_u32_e32 v7, 0x10000, v6
	global_store_dwordx4 v7, v[56:59], s[48:49]
	ds_read2_b32 v[8:9], v4 offset0:24 offset1:57
	ds_read2_b32 v[10:11], v4 offset0:90 offset1:123
	ds_read2_b32 v[12:13], v4 offset0:156 offset1:189
	ds_read2_b32 v[14:15], v4 offset0:222 offset1:255
	s_waitcnt lgkmcnt(0)
	v_cvt_pk_bf16_f32 v60, v8, v9
	v_cvt_pk_bf16_f32 v61, v10, v11
	v_cvt_pk_bf16_f32 v62, v12, v13
	v_cvt_pk_bf16_f32 v63, v14, v15
	v_add_u32_e32 v7, 0x18000, v6
	global_store_dwordx4 v7, v[60:63], s[48:49]
	s_add_i32 s3, s0, 8192
	s_mul_i32 s29, s3, 0x1745e
	s_lshr_b32 s29, s29, 25
	s_mul_i32 s35, s29, 0x160
	s_sub_i32 s35, s3, s35
	s_mul_i32 s58, s29, 0x2c0000
	s_lshl_b32 s59, s35, 7
	s_add_u32 s58, s58, s59
	s_add_u32 s46, s10, s58
	s_addc_u32 s47, s11, 0
	global_load_dwordx4 v[48:51], v2, s[46:47] nt
	v_add_u32_e32 v7, 0x58000, v2
	global_load_dwordx4 v[52:55], v7, s[46:47] nt
	v_add_u32_e32 v7, 0xb0000, v2
	global_load_dwordx4 v[56:59], v7, s[46:47] nt
	v_add_u32_e32 v7, 0x108000, v2
	global_load_dwordx4 v[60:63], v7, s[46:47] nt
	v_add_u32_e32 v7, 0x160000, v2
	global_load_dwordx4 v[64:67], v7, s[46:47] nt
	v_add_u32_e32 v7, 0x1b8000, v2
	global_load_dwordx4 v[68:71], v7, s[46:47] nt
	v_add_u32_e32 v7, 0x210000, v2
	global_load_dwordx4 v[72:75], v7, s[46:47] nt
	v_add_u32_e32 v7, 0x268000, v2
	global_load_dwordx4 v[76:79], v7, s[46:47] nt
	s_waitcnt vmcnt(16)
	ds_write_b32 v3, v80
	ds_write_b32 v3, v81 offset:4
	ds_write_b32 v3, v82 offset:8
	ds_write_b32 v3, v83 offset:12
	ds_write_b32 v3, v84 offset:1056
	ds_write_b32 v3, v85 offset:1060
	ds_write_b32 v3, v86 offset:1064
	ds_write_b32 v3, v87 offset:1068
	ds_write_b32 v3, v88 offset:2112
	ds_write_b32 v3, v89 offset:2116
	ds_write_b32 v3, v90 offset:2120
	ds_write_b32 v3, v91 offset:2124
	ds_write_b32 v3, v92 offset:3168
	ds_write_b32 v3, v93 offset:3172
	ds_write_b32 v3, v94 offset:3176
	ds_write_b32 v3, v95 offset:3180
	ds_write_b32 v3, v96 offset:4224
	ds_write_b32 v3, v97 offset:4228
	ds_write_b32 v3, v98 offset:4232
	ds_write_b32 v3, v99 offset:4236
	ds_write_b32 v3, v100 offset:5280
	ds_write_b32 v3, v101 offset:5284
	ds_write_b32 v3, v102 offset:5288
	ds_write_b32 v3, v103 offset:5292
	ds_write_b32 v3, v104 offset:6336
	ds_write_b32 v3, v105 offset:6340
	ds_write_b32 v3, v106 offset:6344
	ds_write_b32 v3, v107 offset:6348
	ds_write_b32 v3, v108 offset:7392
	ds_write_b32 v3, v109 offset:7396
	ds_write_b32 v3, v110 offset:7400
	ds_write_b32 v3, v111 offset:7404
	s_waitcnt lgkmcnt(0)
	s_add_i32 s3, s0, 6144
	s_mul_i32 s29, s3, 0x1745e
	s_lshr_b32 s29, s29, 25
	s_mul_i32 s35, s29, 0x160
	s_sub_i32 s35, s3, s35
	s_lshl_b32 s58, s35, 17
	s_lshl_b32 s59, s29, 7
	s_add_u32 s58, s58, s59
	s_add_u32 s48, s42, s58
	s_addc_u32 s49, s43, 0
	ds_read2_b32 v[8:9], v4 offset0:0 offset1:33
	ds_read2_b32 v[10:11], v4 offset0:66 offset1:99
	ds_read2_b32 v[12:13], v4 offset0:132 offset1:165
	ds_read2_b32 v[14:15], v4 offset0:198 offset1:231
	s_waitcnt lgkmcnt(0)
	v_cvt_pk_bf16_f32 v80, v8, v9
	v_cvt_pk_bf16_f32 v81, v10, v11
	v_cvt_pk_bf16_f32 v82, v12, v13
	v_cvt_pk_bf16_f32 v83, v14, v15
	global_store_dwordx4 v6, v[80:83], s[48:49]
	ds_read2_b32 v[8:9], v4 offset0:8 offset1:41
	ds_read2_b32 v[10:11], v4 offset0:74 offset1:107
	ds_read2_b32 v[12:13], v4 offset0:140 offset1:173
	ds_read2_b32 v[14:15], v4 offset0:206 offset1:239
	s_waitcnt lgkmcnt(0)
	v_cvt_pk_bf16_f32 v84, v8, v9
	v_cvt_pk_bf16_f32 v85, v10, v11
	v_cvt_pk_bf16_f32 v86, v12, v13
	v_cvt_pk_bf16_f32 v87, v14, v15
	v_add_u32_e32 v7, 0x8000, v6
	global_store_dwordx4 v7, v[84:87], s[48:49]
	ds_read2_b32 v[8:9], v4 offset0:16 offset1:49
	ds_read2_b32 v[10:11], v4 offset0:82 offset1:115
	ds_read2_b32 v[12:13], v4 offset0:148 offset1:181
	ds_read2_b32 v[14:15], v4 offset0:214 offset1:247
	s_waitcnt lgkmcnt(0)
	v_cvt_pk_bf16_f32 v88, v8, v9
	v_cvt_pk_bf16_f32 v89, v10, v11
	v_cvt_pk_bf16_f32 v90, v12, v13
	v_cvt_pk_bf16_f32 v91, v14, v15
	v_add_u32_e32 v7, 0x10000, v6
	global_store_dwordx4 v7, v[88:91], s[48:49]
	ds_read2_b32 v[8:9], v4 offset0:24 offset1:57
	ds_read2_b32 v[10:11], v4 offset0:90 offset1:123
	ds_read2_b32 v[12:13], v4 offset0:156 offset1:189
	ds_read2_b32 v[14:15], v4 offset0:222 offset1:255
	s_waitcnt lgkmcnt(0)
	v_cvt_pk_bf16_f32 v92, v8, v9
	v_cvt_pk_bf16_f32 v93, v10, v11
	v_cvt_pk_bf16_f32 v94, v12, v13
	v_cvt_pk_bf16_f32 v95, v14, v15
	v_add_u32_e32 v7, 0x18000, v6
	global_store_dwordx4 v7, v[92:95], s[48:49]
	s_add_i32 s3, s0, 9216
	s_mul_i32 s29, s3, 0x1745e
	s_lshr_b32 s29, s29, 25
	s_mul_i32 s35, s29, 0x160
	s_sub_i32 s35, s3, s35
	s_mul_i32 s58, s29, 0x2c0000
	s_lshl_b32 s59, s35, 7
	s_add_u32 s58, s58, s59
	s_add_u32 s46, s10, s58
	s_addc_u32 s47, s11, 0
	global_load_dwordx4 v[80:83], v2, s[46:47] nt
	v_add_u32_e32 v7, 0x58000, v2
	global_load_dwordx4 v[84:87], v7, s[46:47] nt
	v_add_u32_e32 v7, 0xb0000, v2
	global_load_dwordx4 v[88:91], v7, s[46:47] nt
	v_add_u32_e32 v7, 0x108000, v2
	global_load_dwordx4 v[92:95], v7, s[46:47] nt
	v_add_u32_e32 v7, 0x160000, v2
	global_load_dwordx4 v[96:99], v7, s[46:47] nt
	v_add_u32_e32 v7, 0x1b8000, v2
	global_load_dwordx4 v[100:103], v7, s[46:47] nt
	v_add_u32_e32 v7, 0x210000, v2
	global_load_dwordx4 v[104:107], v7, s[46:47] nt
	v_add_u32_e32 v7, 0x268000, v2
	global_load_dwordx4 v[108:111], v7, s[46:47] nt
	s_waitcnt vmcnt(16)
	ds_write_b32 v3, v16
	ds_write_b32 v3, v17 offset:4
	ds_write_b32 v3, v18 offset:8
	ds_write_b32 v3, v19 offset:12
	ds_write_b32 v3, v20 offset:1056
	ds_write_b32 v3, v21 offset:1060
	ds_write_b32 v3, v22 offset:1064
	ds_write_b32 v3, v23 offset:1068
	ds_write_b32 v3, v24 offset:2112
	ds_write_b32 v3, v25 offset:2116
	ds_write_b32 v3, v26 offset:2120
	ds_write_b32 v3, v27 offset:2124
	ds_write_b32 v3, v28 offset:3168
	ds_write_b32 v3, v29 offset:3172
	ds_write_b32 v3, v30 offset:3176
	ds_write_b32 v3, v31 offset:3180
	ds_write_b32 v3, v32 offset:4224
	ds_write_b32 v3, v33 offset:4228
	ds_write_b32 v3, v34 offset:4232
	ds_write_b32 v3, v35 offset:4236
	ds_write_b32 v3, v36 offset:5280
	ds_write_b32 v3, v37 offset:5284
	ds_write_b32 v3, v38 offset:5288
	ds_write_b32 v3, v39 offset:5292
	ds_write_b32 v3, v40 offset:6336
	ds_write_b32 v3, v41 offset:6340
	ds_write_b32 v3, v42 offset:6344
	ds_write_b32 v3, v43 offset:6348
	ds_write_b32 v3, v44 offset:7392
	ds_write_b32 v3, v45 offset:7396
	ds_write_b32 v3, v46 offset:7400
	ds_write_b32 v3, v47 offset:7404
	s_waitcnt lgkmcnt(0)
	s_add_i32 s3, s0, 7168
	s_mul_i32 s29, s3, 0x1745e
	s_lshr_b32 s29, s29, 25
	s_mul_i32 s35, s29, 0x160
	s_sub_i32 s35, s3, s35
	s_lshl_b32 s58, s35, 17
	s_lshl_b32 s59, s29, 7
	s_add_u32 s58, s58, s59
	s_add_u32 s48, s42, s58
	s_addc_u32 s49, s43, 0
	ds_read2_b32 v[8:9], v4 offset0:0 offset1:33
	ds_read2_b32 v[10:11], v4 offset0:66 offset1:99
	ds_read2_b32 v[12:13], v4 offset0:132 offset1:165
	ds_read2_b32 v[14:15], v4 offset0:198 offset1:231
	s_waitcnt lgkmcnt(0)
	v_cvt_pk_bf16_f32 v16, v8, v9
	v_cvt_pk_bf16_f32 v17, v10, v11
	v_cvt_pk_bf16_f32 v18, v12, v13
	v_cvt_pk_bf16_f32 v19, v14, v15
	global_store_dwordx4 v6, v[16:19], s[48:49]
	ds_read2_b32 v[8:9], v4 offset0:8 offset1:41
	ds_read2_b32 v[10:11], v4 offset0:74 offset1:107
	ds_read2_b32 v[12:13], v4 offset0:140 offset1:173
	ds_read2_b32 v[14:15], v4 offset0:206 offset1:239
	s_waitcnt lgkmcnt(0)
	v_cvt_pk_bf16_f32 v20, v8, v9
	v_cvt_pk_bf16_f32 v21, v10, v11
	v_cvt_pk_bf16_f32 v22, v12, v13
	v_cvt_pk_bf16_f32 v23, v14, v15
	v_add_u32_e32 v7, 0x8000, v6
	global_store_dwordx4 v7, v[20:23], s[48:49]
	ds_read2_b32 v[8:9], v4 offset0:16 offset1:49
	ds_read2_b32 v[10:11], v4 offset0:82 offset1:115
	ds_read2_b32 v[12:13], v4 offset0:148 offset1:181
	ds_read2_b32 v[14:15], v4 offset0:214 offset1:247
	s_waitcnt lgkmcnt(0)
	v_cvt_pk_bf16_f32 v24, v8, v9
	v_cvt_pk_bf16_f32 v25, v10, v11
	v_cvt_pk_bf16_f32 v26, v12, v13
	v_cvt_pk_bf16_f32 v27, v14, v15
	v_add_u32_e32 v7, 0x10000, v6
	global_store_dwordx4 v7, v[24:27], s[48:49]
	ds_read2_b32 v[8:9], v4 offset0:24 offset1:57
	ds_read2_b32 v[10:11], v4 offset0:90 offset1:123
	ds_read2_b32 v[12:13], v4 offset0:156 offset1:189
	ds_read2_b32 v[14:15], v4 offset0:222 offset1:255
	s_waitcnt lgkmcnt(0)
	v_cvt_pk_bf16_f32 v28, v8, v9
	v_cvt_pk_bf16_f32 v29, v10, v11
	v_cvt_pk_bf16_f32 v30, v12, v13
	v_cvt_pk_bf16_f32 v31, v14, v15
	v_add_u32_e32 v7, 0x18000, v6
	global_store_dwordx4 v7, v[28:31], s[48:49]
	s_waitcnt vmcnt(8)
	ds_write_b32 v3, v48
	ds_write_b32 v3, v49 offset:4
	ds_write_b32 v3, v50 offset:8
	ds_write_b32 v3, v51 offset:12
	ds_write_b32 v3, v52 offset:1056
	ds_write_b32 v3, v53 offset:1060
	ds_write_b32 v3, v54 offset:1064
	ds_write_b32 v3, v55 offset:1068
	ds_write_b32 v3, v56 offset:2112
	ds_write_b32 v3, v57 offset:2116
	ds_write_b32 v3, v58 offset:2120
	ds_write_b32 v3, v59 offset:2124
	ds_write_b32 v3, v60 offset:3168
	ds_write_b32 v3, v61 offset:3172
	ds_write_b32 v3, v62 offset:3176
	ds_write_b32 v3, v63 offset:3180
	ds_write_b32 v3, v64 offset:4224
	ds_write_b32 v3, v65 offset:4228
	ds_write_b32 v3, v66 offset:4232
	ds_write_b32 v3, v67 offset:4236
	ds_write_b32 v3, v68 offset:5280
	ds_write_b32 v3, v69 offset:5284
	ds_write_b32 v3, v70 offset:5288
	ds_write_b32 v3, v71 offset:5292
	ds_write_b32 v3, v72 offset:6336
	ds_write_b32 v3, v73 offset:6340
	ds_write_b32 v3, v74 offset:6344
	ds_write_b32 v3, v75 offset:6348
	ds_write_b32 v3, v76 offset:7392
	ds_write_b32 v3, v77 offset:7396
	ds_write_b32 v3, v78 offset:7400
	ds_write_b32 v3, v79 offset:7404
	s_waitcnt lgkmcnt(0)
	s_add_i32 s3, s0, 8192
	s_mul_i32 s29, s3, 0x1745e
	s_lshr_b32 s29, s29, 25
	s_mul_i32 s35, s29, 0x160
	s_sub_i32 s35, s3, s35
	s_lshl_b32 s58, s35, 17
	s_lshl_b32 s59, s29, 7
	s_add_u32 s58, s58, s59
	s_add_u32 s48, s42, s58
	s_addc_u32 s49, s43, 0
	ds_read2_b32 v[8:9], v4 offset0:0 offset1:33
	ds_read2_b32 v[10:11], v4 offset0:66 offset1:99
	ds_read2_b32 v[12:13], v4 offset0:132 offset1:165
	ds_read2_b32 v[14:15], v4 offset0:198 offset1:231
	s_waitcnt lgkmcnt(0)
	v_cvt_pk_bf16_f32 v48, v8, v9
	v_cvt_pk_bf16_f32 v49, v10, v11
	v_cvt_pk_bf16_f32 v50, v12, v13
	v_cvt_pk_bf16_f32 v51, v14, v15
	global_store_dwordx4 v6, v[48:51], s[48:49]
	ds_read2_b32 v[8:9], v4 offset0:8 offset1:41
	ds_read2_b32 v[10:11], v4 offset0:74 offset1:107
	ds_read2_b32 v[12:13], v4 offset0:140 offset1:173
	ds_read2_b32 v[14:15], v4 offset0:206 offset1:239
	s_waitcnt lgkmcnt(0)
	v_cvt_pk_bf16_f32 v52, v8, v9
	v_cvt_pk_bf16_f32 v53, v10, v11
	v_cvt_pk_bf16_f32 v54, v12, v13
	v_cvt_pk_bf16_f32 v55, v14, v15
	v_add_u32_e32 v7, 0x8000, v6
	global_store_dwordx4 v7, v[52:55], s[48:49]
	ds_read2_b32 v[8:9], v4 offset0:16 offset1:49
	ds_read2_b32 v[10:11], v4 offset0:82 offset1:115
	ds_read2_b32 v[12:13], v4 offset0:148 offset1:181
	ds_read2_b32 v[14:15], v4 offset0:214 offset1:247
	s_waitcnt lgkmcnt(0)
	v_cvt_pk_bf16_f32 v56, v8, v9
	v_cvt_pk_bf16_f32 v57, v10, v11
	v_cvt_pk_bf16_f32 v58, v12, v13
	v_cvt_pk_bf16_f32 v59, v14, v15
	v_add_u32_e32 v7, 0x10000, v6
	global_store_dwordx4 v7, v[56:59], s[48:49]
	ds_read2_b32 v[8:9], v4 offset0:24 offset1:57
	ds_read2_b32 v[10:11], v4 offset0:90 offset1:123
	ds_read2_b32 v[12:13], v4 offset0:156 offset1:189
	ds_read2_b32 v[14:15], v4 offset0:222 offset1:255
	s_waitcnt lgkmcnt(0)
	v_cvt_pk_bf16_f32 v60, v8, v9
	v_cvt_pk_bf16_f32 v61, v10, v11
	v_cvt_pk_bf16_f32 v62, v12, v13
	v_cvt_pk_bf16_f32 v63, v14, v15
	v_add_u32_e32 v7, 0x18000, v6
	global_store_dwordx4 v7, v[60:63], s[48:49]
	s_waitcnt vmcnt(0)
	ds_write_b32 v3, v80
	ds_write_b32 v3, v81 offset:4
	ds_write_b32 v3, v82 offset:8
	ds_write_b32 v3, v83 offset:12
	ds_write_b32 v3, v84 offset:1056
	ds_write_b32 v3, v85 offset:1060
	ds_write_b32 v3, v86 offset:1064
	ds_write_b32 v3, v87 offset:1068
	ds_write_b32 v3, v88 offset:2112
	ds_write_b32 v3, v89 offset:2116
	ds_write_b32 v3, v90 offset:2120
	ds_write_b32 v3, v91 offset:2124
	ds_write_b32 v3, v92 offset:3168
	ds_write_b32 v3, v93 offset:3172
	ds_write_b32 v3, v94 offset:3176
	ds_write_b32 v3, v95 offset:3180
	ds_write_b32 v3, v96 offset:4224
	ds_write_b32 v3, v97 offset:4228
	ds_write_b32 v3, v98 offset:4232
	ds_write_b32 v3, v99 offset:4236
	ds_write_b32 v3, v100 offset:5280
	ds_write_b32 v3, v101 offset:5284
	ds_write_b32 v3, v102 offset:5288
	ds_write_b32 v3, v103 offset:5292
	ds_write_b32 v3, v104 offset:6336
	ds_write_b32 v3, v105 offset:6340
	ds_write_b32 v3, v106 offset:6344
	ds_write_b32 v3, v107 offset:6348
	ds_write_b32 v3, v108 offset:7392
	ds_write_b32 v3, v109 offset:7396
	ds_write_b32 v3, v110 offset:7400
	ds_write_b32 v3, v111 offset:7404
	s_waitcnt lgkmcnt(0)
	s_add_i32 s3, s0, 9216
	s_mul_i32 s29, s3, 0x1745e
	s_lshr_b32 s29, s29, 25
	s_mul_i32 s35, s29, 0x160
	s_sub_i32 s35, s3, s35
	s_lshl_b32 s58, s35, 17
	s_lshl_b32 s59, s29, 7
	s_add_u32 s58, s58, s59
	s_add_u32 s48, s42, s58
	s_addc_u32 s49, s43, 0
	ds_read2_b32 v[8:9], v4 offset0:0 offset1:33
	ds_read2_b32 v[10:11], v4 offset0:66 offset1:99
	ds_read2_b32 v[12:13], v4 offset0:132 offset1:165
	ds_read2_b32 v[14:15], v4 offset0:198 offset1:231
	s_waitcnt lgkmcnt(0)
	v_cvt_pk_bf16_f32 v80, v8, v9
	v_cvt_pk_bf16_f32 v81, v10, v11
	v_cvt_pk_bf16_f32 v82, v12, v13
	v_cvt_pk_bf16_f32 v83, v14, v15
	global_store_dwordx4 v6, v[80:83], s[48:49]
	ds_read2_b32 v[8:9], v4 offset0:8 offset1:41
	ds_read2_b32 v[10:11], v4 offset0:74 offset1:107
	ds_read2_b32 v[12:13], v4 offset0:140 offset1:173
	ds_read2_b32 v[14:15], v4 offset0:206 offset1:239
	s_waitcnt lgkmcnt(0)
	v_cvt_pk_bf16_f32 v84, v8, v9
	v_cvt_pk_bf16_f32 v85, v10, v11
	v_cvt_pk_bf16_f32 v86, v12, v13
	v_cvt_pk_bf16_f32 v87, v14, v15
	v_add_u32_e32 v7, 0x8000, v6
	global_store_dwordx4 v7, v[84:87], s[48:49]
	ds_read2_b32 v[8:9], v4 offset0:16 offset1:49
	ds_read2_b32 v[10:11], v4 offset0:82 offset1:115
	ds_read2_b32 v[12:13], v4 offset0:148 offset1:181
	ds_read2_b32 v[14:15], v4 offset0:214 offset1:247
	s_waitcnt lgkmcnt(0)
	v_cvt_pk_bf16_f32 v88, v8, v9
	v_cvt_pk_bf16_f32 v89, v10, v11
	v_cvt_pk_bf16_f32 v90, v12, v13
	v_cvt_pk_bf16_f32 v91, v14, v15
	v_add_u32_e32 v7, 0x10000, v6
	global_store_dwordx4 v7, v[88:91], s[48:49]
	ds_read2_b32 v[8:9], v4 offset0:24 offset1:57
	ds_read2_b32 v[10:11], v4 offset0:90 offset1:123
	ds_read2_b32 v[12:13], v4 offset0:156 offset1:189
	ds_read2_b32 v[14:15], v4 offset0:222 offset1:255
	s_waitcnt lgkmcnt(0)
	v_cvt_pk_bf16_f32 v92, v8, v9
	v_cvt_pk_bf16_f32 v93, v10, v11
	v_cvt_pk_bf16_f32 v94, v12, v13
	v_cvt_pk_bf16_f32 v95, v14, v15
	v_add_u32_e32 v7, 0x18000, v6
	global_store_dwordx4 v7, v[92:95], s[48:49]
	s_branch .LBB0_376
